# GroupNorm phase: loop-invariant gain/bias vectors loaded once before the row loop; the per-group vmcnt(0) drains (which also waited for the group's own store) removed
# speedup vs baseline: 1.0063x; 1.0063x over previous
.Lser_exit:
	s_nop 0
	s_nop 0
	s_nop 0
	s_nop 0
	s_nop 0
	s_nop 0
	s_nop 0
	s_nop 0
	s_nop 0
	s_nop 0
	s_nop 0
	s_nop 0
	s_nop 0
	s_nop 0
	s_nop 0
	s_nop 0
	s_nop 0
	s_nop 0
	s_nop 0
	s_nop 0
	v_lshlrev_b32_e32 v157, 2, v0

.LBB0_625:
	s_cmp_lt_i32 s34, 7
	s_cselect_b64 s[8:9], -1, 0
	s_and_b64 s[6:7], s[8:9], s[6:7]
	s_andn2_b64 vcc, exec, s[6:7]
	s_cbranch_vccnz .LBB0_630
	s_lshl_b32 s12, s2, 3
	v_or_b32_e32 v1, s12, v130
	s_movk_i32 s3, 0x2000
	v_cmp_gt_i32_e32 vcc, s3, v1
	s_and_saveexec_b64 s[6:7], vcc
	s_cbranch_execz .LBB0_629
	v_lshlrev_b32_e32 v2, 4, v0
	s_waitcnt vmcnt(15)
	v_mov_b32_e32 v27, 0
	v_lshlrev_b32_e32 v8, 3, v0
	s_load_dword s3, s[0:1], 0xd8
	s_waitcnt vmcnt(14)
	v_bfe_u32 v34, v0, 4, 2
	v_and_b32_e32 v26, 0x3f0, v2
	v_mov_b32_e32 v131, v27
	s_ashr_i32 s13, s12, 31
	v_and_b32_e32 v8, 0x78, v8
	v_lshl_add_u64 v[2:3], s[60:61], 0, v[26:27]
	v_lshl_add_u64 v[4:5], s[62:63], 0, v[26:27]
	s_waitcnt vmcnt(0)
	v_lshl_add_u64 v[22:23], v[130:131], 0, s[12:13]
	v_lshl_or_b32 v26, v34, 7, v8
	s_movk_i32 s16, 0x1800
	v_or_b32_e32 v20, 0x600, v26
	v_mad_u64_u32 v[30:31], s[14:15], v22, s16, 0
	v_or_b32_e32 v24, 0x400, v26
	v_mov_b32_e32 v21, v27
	v_mad_i32_i24 v33, v23, s16, v31
	v_or_b32_e32 v32, v30, v20
	s_mov_b64 s[18:19], 0x1000
	v_lshlrev_b64 v[6:7], 11, v[22:23]
	v_mov_b32_e32 v25, v27
	v_lshl_add_u64 v[18:19], s[70:71], 0, v[20:21]
	v_lshl_add_u64 v[20:21], v[32:33], 0, s[18:19]
	v_lshlrev_b64 v[22:23], 6, v[22:23]
	v_or_b32_e32 v32, v30, v24
	s_waitcnt lgkmcnt(0)
	s_lshl_b32 s10, s3, 3
	v_or_b32_e32 v28, 0x200, v26
	v_and_b32_e32 v12, 63, v0
	v_mov_b32_e32 v13, 0x3000400
	v_lshl_add_u64 v[16:17], s[70:71], 0, v[24:25]
	v_lshl_or_b32 v22, v34, 2, v22
	v_lshl_add_u64 v[24:25], v[32:33], 0, s[18:19]
	v_or_b32_e32 v32, v30, v26
	v_lshl_add_u64 v[8:9], s[70:71], 0, v[26:27]
	s_ashr_i32 s11, s10, 31
	v_mov_b32_e32 v29, v27
	v_lshl_or_b32 v12, v12, 3, v13
	v_mov_b32_e32 v13, v27
	v_lshl_add_u64 v[22:23], s[70:71], 0, v[22:23]
	s_mov_b64 s[16:17], 0x15c08020
	v_lshl_add_u64 v[26:27], v[32:33], 0, s[18:19]
	v_or_b32_e32 v32, v30, v28
	s_lshl_b64 s[12:13], s[10:11], 11
	v_lshl_add_u64 v[10:11], s[70:71], 0, v[28:29]
	v_lshl_add_u64 v[14:15], s[68:69], 0, v[6:7]
	s_mul_i32 s14, s3, 0xc000
	s_mul_hi_i32 s15, s10, 0x1800
	v_lshl_add_u64 v[22:23], v[22:23], 0, s[16:17]
	s_lshl_b64 s[16:17], s[10:11], 6
	v_lshl_add_u64 v[28:29], v[32:33], 0, s[18:19]
	s_mov_b64 s[18:19], 0
	s_mov_b32 s3, 0x14a08000
	s_mov_b32 s11, 0xb900000
	s_mov_b32 s20, 0x3c800000
	s_mov_b32 s22, 0x3a27c5ac
	s_mov_b32 s21, 0x800000
	s_movk_i32 s23, 0x1fff
	global_load_dwordx4 v[140:143], v[2:3], off
	global_load_dwordx4 v[144:147], v[4:5], off
	global_load_dwordx4 v[148:151], v[2:3], off offset:1024
	global_load_dwordx4 v[152:155], v[4:5], off offset:1024
	global_load_dwordx4 v[156:159], v[2:3], off offset:2048
	global_load_dwordx4 v[160:163], v[4:5], off offset:2048
	global_load_dwordx4 v[164:167], v[2:3], off offset:3072
	global_load_dwordx4 v[168:171], v[4:5], off offset:3072
	s_waitcnt vmcnt(0)
.LBB0_628:
	v_lshl_add_u64 v[34:35], v[8:9], 0, v[6:7]
	v_add_co_u32_e32 v60, vcc, 0x14a08000, v34
	v_lshl_add_u64 v[46:47], s[68:69], 0, v[26:27]
	s_nop 0
	v_addc_co_u32_e32 v61, vcc, 0, v35, vcc
	v_add_co_u32_e32 v34, vcc, 0xb900000, v34
	v_lshl_add_u64 v[48:49], v[10:11], 0, v[6:7]
	v_lshl_add_u64 v[50:51], s[68:69], 0, v[28:29]
	v_addc_co_u32_e32 v35, vcc, 0, v35, vcc
	v_lshl_add_u64 v[54:55], s[68:69], 0, v[24:25]
	v_lshl_add_u64 v[58:59], s[68:69], 0, v[20:21]
	global_load_dword v72, v[22:23], off offset:-32
	global_load_dword v73, v[22:23], off offset:-16
	global_load_dword v74, v[22:23], off
	global_load_dword v75, v[22:23], off offset:16
	v_mov_b32_e32 v38, v140
	v_mov_b32_e32 v39, v141
	v_mov_b32_e32 v40, v142
	v_mov_b32_e32 v41, v143
	v_mov_b32_e32 v42, v144
	v_mov_b32_e32 v43, v145
	v_mov_b32_e32 v44, v146
	v_mov_b32_e32 v45, v147
	global_load_dwordx2 v[62:63], v[46:47], off
	global_load_dwordx2 v[64:65], v[50:51], off
	global_load_dwordx2 v[66:67], v[54:55], off
	global_load_dwordx2 v[32:33], v[58:59], off
	v_add_co_u32_e32 v50, vcc, s3, v48
	global_load_dwordx2 v[46:47], v[60:61], off
	s_nop 0
	v_addc_co_u32_e32 v51, vcc, 0, v49, vcc
	global_load_dwordx2 v[54:55], v[34:35], off
	v_add_co_u32_e32 v34, vcc, s11, v48
	global_load_dwordx2 v[50:51], v[50:51], off
	v_lshl_add_u64 v[52:53], v[16:17], 0, v[6:7]
	v_addc_co_u32_e32 v35, vcc, 0, v49, vcc
	v_add_co_u32_e32 v48, vcc, s3, v52
	global_load_dwordx2 v[58:59], v[34:35], off
	s_nop 0
	v_addc_co_u32_e32 v49, vcc, 0, v53, vcc
	v_add_co_u32_e32 v34, vcc, s11, v52
	v_lshl_add_u64 v[56:57], v[18:19], 0, v[6:7]
	s_nop 0
	v_addc_co_u32_e32 v35, vcc, 0, v53, vcc
	v_add_co_u32_e32 v52, vcc, s3, v56
	global_load_dwordx2 v[48:49], v[48:49], off
	s_nop 0
	global_load_dwordx2 v[60:61], v[34:35], off
	v_addc_co_u32_e32 v53, vcc, 0, v57, vcc
	v_add_co_u32_e32 v34, vcc, s11, v56
	v_mov_b64_e32 v[36:37], s[22:23]
	s_nop 0
	v_addc_co_u32_e32 v35, vcc, 0, v57, vcc
	v_lshl_add_u64 v[30:31], v[14:15], 0, v[12:13]
	global_load_dwordx2 v[52:53], v[52:53], off
	s_nop 0
	global_load_dwordx2 v[34:35], v[34:35], off
	v_add_u32_e32 v1, s10, v1
	v_lshl_add_u64 v[8:9], v[8:9], 0, s[12:13]
	v_lshl_add_u64 v[10:11], v[10:11], 0, s[12:13]
	v_lshl_add_u64 v[12:13], v[12:13], 0, s[12:13]
	v_lshl_add_u64 v[16:17], v[16:17], 0, s[12:13]
	v_lshl_add_u64 v[18:19], v[18:19], 0, s[12:13]
	v_lshl_add_u64 v[20:21], v[20:21], 0, s[14:15]
	v_lshl_add_u64 v[22:23], v[22:23], 0, s[16:17]
	v_lshl_add_u64 v[24:25], v[24:25], 0, s[14:15]
	v_lshl_add_u64 v[26:27], v[26:27], 0, s[14:15]
	v_lshl_add_u64 v[28:29], v[28:29], 0, s[14:15]
	s_waitcnt vmcnt(11)
	v_lshlrev_b32_e32 v76, 16, v62
	v_and_b32_e32 v77, 0xffff0000, v62
	v_lshlrev_b32_e32 v78, 16, v63
	v_and_b32_e32 v79, 0xffff0000, v63
	s_waitcnt vmcnt(7)
	v_lshlrev_b32_e32 v57, 16, v47
	v_lshlrev_b32_e32 v56, 16, v46
	v_and_b32_e32 v47, 0xffff0000, v47
	v_and_b32_e32 v46, 0xffff0000, v46
	v_pk_add_f32 v[62:63], v[56:57], v[46:47]
	s_waitcnt vmcnt(6)
	v_lshlrev_b32_e32 v80, 16, v54
	v_and_b32_e32 v81, 0xffff0000, v54
	v_lshlrev_b32_e32 v82, 16, v55
	v_and_b32_e32 v83, 0xffff0000, v55
	v_add_f32_e32 v62, v62, v63
	s_waitcnt vmcnt(5)
	v_lshlrev_b32_e32 v55, 16, v51
	v_lshlrev_b32_e32 v54, 16, v50
	v_and_b32_e32 v51, 0xffff0000, v51
	v_and_b32_e32 v50, 0xffff0000, v50
	v_add_f32_dpp v68, v62, v62 quad_perm:[1,0,3,2] row_mask:0xf bank_mask:0xf bound_ctrl:1
	v_pk_add_f32 v[62:63], v[54:55], v[50:51]
	s_nop 0
	v_add_f32_dpp v68, v68, v68 quad_perm:[2,3,0,1] row_mask:0xf bank_mask:0xf bound_ctrl:1
	v_add_f32_e32 v62, v62, v63
	s_nop 0
	v_add_f32_dpp v63, v68, v68 row_half_mirror row_mask:0xf bank_mask:0xf bound_ctrl:1
	v_add_f32_dpp v62, v62, v62 quad_perm:[1,0,3,2] row_mask:0xf bank_mask:0xf bound_ctrl:1
	s_nop 0
	v_add_f32_dpp v63, v63, v63 row_mirror row_mask:0xf bank_mask:0xf bound_ctrl:1
	v_add_f32_dpp v68, v62, v62 quad_perm:[2,3,0,1] row_mask:0xf bank_mask:0xf bound_ctrl:1
	v_mul_f32_e32 v62, 0x3c800000, v63
	s_nop 0
	v_add_f32_dpp v63, v68, v68 row_half_mirror row_mask:0xf bank_mask:0xf bound_ctrl:1
	v_pk_add_f32 v[46:47], v[46:47], v[62:63] op_sel_hi:[1,0] neg_lo:[0,1] neg_hi:[0,1]
	v_pk_add_f32 v[56:57], v[56:57], v[62:63] op_sel_hi:[1,0] neg_lo:[0,1] neg_hi:[0,1]
	v_add_f32_dpp v68, v63, v63 row_mirror row_mask:0xf bank_mask:0xf bound_ctrl:1
	v_mul_f32_e32 v68, 0x3c800000, v68
	v_pk_add_f32 v[50:51], v[50:51], v[68:69] op_sel_hi:[1,0] neg_lo:[0,1] neg_hi:[0,1]
	v_pk_mul_f32 v[62:63], v[46:47], v[46:47]
	v_pk_add_f32 v[54:55], v[54:55], v[68:69] op_sel_hi:[1,0] neg_lo:[0,1] neg_hi:[0,1]
	v_pk_mul_f32 v[68:69], v[50:51], v[50:51]
	v_pk_fma_f32 v[62:63], v[56:57], v[56:57], v[62:63]
	v_pk_fma_f32 v[68:69], v[54:55], v[54:55], v[68:69]
	v_mov_b32_e32 v71, v62
	v_mov_b32_e32 v70, v68
	v_mov_b32_e32 v62, v69
	v_pk_add_f32 v[62:63], v[70:71], v[62:63]
	s_waitcnt vmcnt(4)
	v_lshlrev_b32_e32 v71, 16, v58
	v_and_b32_e32 v58, 0xffff0000, v58
	v_mov_b32_dpp v69, v63 quad_perm:[1,0,3,2] row_mask:0xf bank_mask:0xf bound_ctrl:1
	v_mov_b32_dpp v68, v62 quad_perm:[1,0,3,2] row_mask:0xf bank_mask:0xf bound_ctrl:1
	v_pk_add_f32 v[62:63], v[62:63], v[68:69]
	v_lshlrev_b32_e32 v70, 16, v67
	v_and_b32_e32 v67, 0xffff0000, v67
	v_mov_b32_dpp v69, v63 quad_perm:[2,3,0,1] row_mask:0xf bank_mask:0xf bound_ctrl:1
	v_mov_b32_dpp v68, v62 quad_perm:[2,3,0,1] row_mask:0xf bank_mask:0xf bound_ctrl:1
	v_pk_add_f32 v[62:63], v[62:63], v[68:69]
	s_nop 1
	v_mov_b32_dpp v69, v63 row_half_mirror row_mask:0xf bank_mask:0xf bound_ctrl:1
	v_mov_b32_dpp v68, v62 row_half_mirror row_mask:0xf bank_mask:0xf bound_ctrl:1
	v_pk_add_f32 v[62:63], v[62:63], v[68:69]
	s_nop 1
	v_mov_b32_dpp v69, v63 row_mirror row_mask:0xf bank_mask:0xf bound_ctrl:1
	v_mov_b32_dpp v68, v62 row_mirror row_mask:0xf bank_mask:0xf bound_ctrl:1
	v_pk_add_f32 v[62:63], v[62:63], v[68:69]
	v_lshlrev_b32_e32 v69, 16, v66
	v_pk_fma_f32 v[62:63], v[62:63], s[20:21], v[36:37] op_sel_hi:[1,0,0]
	v_and_b32_e32 v66, 0xffff0000, v66
	v_mul_f32_e32 v68, 0x4b800000, v63
	v_cmp_gt_f32_e32 vcc, s21, v63
	s_nop 1
	v_cndmask_b32_e32 v63, v63, v68, vcc
	v_rsq_f32_e32 v63, v63
	s_nop 0
	v_mul_f32_e32 v68, 0x45800000, v63
	v_cndmask_b32_e32 v63, v63, v68, vcc
	v_mul_f32_e32 v56, v56, v63
	v_mul_f32_e32 v46, v46, v63
	v_mul_f32_e32 v57, v57, v63
	v_mul_f32_e32 v47, v47, v63
	v_fma_f32 v38, v38, v56, v42
	v_fma_f32 v39, v39, v46, v43
	v_fma_f32 v40, v40, v57, v44
	v_fmac_f32_e32 v45, v41, v47
	v_fmac_f32_e32 v38, v72, v76
	v_fmac_f32_e32 v39, v72, v77
	v_fmac_f32_e32 v40, v72, v78
	v_fmac_f32_e32 v45, v72, v79
	v_mul_f32_e32 v38, v38, v80
	v_mul_f32_e32 v39, v39, v81
	v_mul_f32_e32 v40, v40, v82
	v_mul_f32_e32 v41, v45, v83
	v_cvt_pk_bf16_f32 v38, v38, v39
	v_cvt_pk_bf16_f32 v39, v40, v41
	global_store_dwordx2 v[30:31], v[38:39], off offset:-1024
	s_nop 1
	v_mov_b32_e32 v38, v148
	v_mov_b32_e32 v39, v149
	v_mov_b32_e32 v40, v150
	v_mov_b32_e32 v41, v151
	s_nop 0
	v_mov_b32_e32 v42, v152
	v_mov_b32_e32 v43, v153
	v_mov_b32_e32 v44, v154
	v_mov_b32_e32 v45, v155
	v_mul_f32_e32 v77, 0x4b800000, v62
	v_cmp_gt_f32_e32 vcc, s21, v62
	v_lshlrev_b32_e32 v63, 16, v64
	v_and_b32_e32 v64, 0xffff0000, v64
	v_cndmask_b32_e32 v62, v62, v77, vcc
	v_rsq_f32_e32 v62, v62
	v_lshlrev_b32_e32 v68, 16, v65
	v_and_b32_e32 v65, 0xffff0000, v65
	v_lshlrev_b32_e32 v72, 16, v59
	v_mul_f32_e32 v77, 0x45800000, v62
	v_cndmask_b32_e32 v62, v62, v77, vcc
	v_mul_f32_e32 v54, v54, v62
	v_mul_f32_e32 v50, v50, v62
	v_mul_f32_e32 v55, v55, v62
	v_mul_f32_e32 v51, v51, v62
	v_and_b32_e32 v59, 0xffff0000, v59
	s_waitcnt vmcnt(4)
	v_lshlrev_b32_e32 v47, 16, v49
	v_lshlrev_b32_e32 v46, 16, v48
	v_and_b32_e32 v49, 0xffff0000, v49
	v_and_b32_e32 v48, 0xffff0000, v48
	v_pk_add_f32 v[56:57], v[46:47], v[48:49]
	s_waitcnt vmcnt(3)
	v_lshlrev_b32_e32 v76, 16, v60
	v_and_b32_e32 v60, 0xffff0000, v60
	v_lshlrev_b32_e32 v62, 16, v61
	v_and_b32_e32 v61, 0xffff0000, v61
	s_waitcnt vmcnt(1)
	v_fma_f32 v38, v38, v54, v42
	v_fma_f32 v39, v39, v50, v43
	v_fma_f32 v40, v40, v55, v44
	v_fmac_f32_e32 v45, v41, v51
	v_fmac_f32_e32 v38, v73, v63
	v_fmac_f32_e32 v39, v73, v64
	v_fmac_f32_e32 v40, v73, v68
	v_fmac_f32_e32 v45, v73, v65
	v_mul_f32_e32 v38, v38, v71
	v_mul_f32_e32 v39, v39, v58
	v_mul_f32_e32 v40, v40, v72
	v_mul_f32_e32 v41, v45, v59
	v_cvt_pk_bf16_f32 v38, v38, v39
	v_cvt_pk_bf16_f32 v39, v40, v41
	global_store_dwordx2 v[30:31], v[38:39], off offset:-512
	s_nop 1
	v_mov_b32_e32 v38, v156
	v_mov_b32_e32 v39, v157
	v_mov_b32_e32 v40, v158
	v_mov_b32_e32 v41, v159
	s_nop 0
	v_mov_b32_e32 v42, v160
	v_mov_b32_e32 v43, v161
	v_mov_b32_e32 v44, v162
	v_mov_b32_e32 v45, v163
	v_add_f32_e32 v54, v56, v57
	v_lshlrev_b32_e32 v51, 16, v53
	v_lshlrev_b32_e32 v50, 16, v52
	v_and_b32_e32 v53, 0xffff0000, v53
	v_and_b32_e32 v52, 0xffff0000, v52
	v_add_f32_dpp v56, v54, v54 quad_perm:[1,0,3,2] row_mask:0xf bank_mask:0xf bound_ctrl:1
	v_pk_add_f32 v[54:55], v[50:51], v[52:53]
	s_nop 0
	v_add_f32_dpp v56, v56, v56 quad_perm:[2,3,0,1] row_mask:0xf bank_mask:0xf bound_ctrl:1
	v_add_f32_e32 v54, v54, v55
	s_nop 0
	v_add_f32_dpp v55, v56, v56 row_half_mirror row_mask:0xf bank_mask:0xf bound_ctrl:1
	v_add_f32_dpp v54, v54, v54 quad_perm:[1,0,3,2] row_mask:0xf bank_mask:0xf bound_ctrl:1
	s_nop 0
	v_add_f32_dpp v55, v55, v55 row_mirror row_mask:0xf bank_mask:0xf bound_ctrl:1
	v_add_f32_dpp v56, v54, v54 quad_perm:[2,3,0,1] row_mask:0xf bank_mask:0xf bound_ctrl:1
	v_mul_f32_e32 v54, 0x3c800000, v55
	s_nop 0
	v_add_f32_dpp v55, v56, v56 row_half_mirror row_mask:0xf bank_mask:0xf bound_ctrl:1
	v_pk_add_f32 v[48:49], v[48:49], v[54:55] op_sel_hi:[1,0] neg_lo:[0,1] neg_hi:[0,1]
	v_pk_add_f32 v[46:47], v[46:47], v[54:55] op_sel_hi:[1,0] neg_lo:[0,1] neg_hi:[0,1]
	v_add_f32_dpp v56, v55, v55 row_mirror row_mask:0xf bank_mask:0xf bound_ctrl:1
	v_mul_f32_e32 v56, 0x3c800000, v56
	v_pk_add_f32 v[52:53], v[52:53], v[56:57] op_sel_hi:[1,0] neg_lo:[0,1] neg_hi:[0,1]
	v_pk_mul_f32 v[54:55], v[48:49], v[48:49]
	v_pk_add_f32 v[50:51], v[50:51], v[56:57] op_sel_hi:[1,0] neg_lo:[0,1] neg_hi:[0,1]
	v_pk_mul_f32 v[56:57], v[52:53], v[52:53]
	v_pk_fma_f32 v[54:55], v[46:47], v[46:47], v[54:55]
	v_pk_fma_f32 v[56:57], v[50:51], v[50:51], v[56:57]
	v_mov_b32_e32 v59, v54
	v_mov_b32_e32 v58, v56
	v_mov_b32_e32 v54, v57
	v_pk_add_f32 v[54:55], v[58:59], v[54:55]
	s_nop 1
	v_mov_b32_dpp v57, v55 quad_perm:[1,0,3,2] row_mask:0xf bank_mask:0xf bound_ctrl:1
	v_mov_b32_dpp v56, v54 quad_perm:[1,0,3,2] row_mask:0xf bank_mask:0xf bound_ctrl:1
	v_pk_add_f32 v[54:55], v[54:55], v[56:57]
	s_nop 1
	v_mov_b32_dpp v57, v55 quad_perm:[2,3,0,1] row_mask:0xf bank_mask:0xf bound_ctrl:1
	v_mov_b32_dpp v56, v54 quad_perm:[2,3,0,1] row_mask:0xf bank_mask:0xf bound_ctrl:1
	v_pk_add_f32 v[54:55], v[54:55], v[56:57]
	s_nop 1
	v_mov_b32_dpp v57, v55 row_half_mirror row_mask:0xf bank_mask:0xf bound_ctrl:1
	v_mov_b32_dpp v56, v54 row_half_mirror row_mask:0xf bank_mask:0xf bound_ctrl:1
	v_pk_add_f32 v[54:55], v[54:55], v[56:57]
	s_nop 1
	v_mov_b32_dpp v57, v55 row_mirror row_mask:0xf bank_mask:0xf bound_ctrl:1
	v_mov_b32_dpp v56, v54 row_mirror row_mask:0xf bank_mask:0xf bound_ctrl:1
	v_pk_add_f32 v[54:55], v[54:55], v[56:57]
	s_nop 0
	v_pk_fma_f32 v[54:55], v[54:55], s[20:21], v[36:37] op_sel_hi:[1,0,0]
	s_nop 0
	v_mul_f32_e32 v36, 0x4b800000, v55
	v_cmp_gt_f32_e32 vcc, s21, v55
	s_nop 1
	v_cndmask_b32_e32 v36, v55, v36, vcc
	v_rsq_f32_e32 v36, v36
	s_nop 0
	v_mul_f32_e32 v37, 0x45800000, v36
	v_cndmask_b32_e32 v36, v36, v37, vcc
	v_mul_f32_e32 v37, v46, v36
	v_mul_f32_e32 v46, v48, v36
	v_mul_f32_e32 v47, v47, v36
	v_mul_f32_e32 v36, v49, v36
	v_cmp_lt_i32_e32 vcc, s23, v1
	s_or_b64 s[18:19], vcc, s[18:19]
	v_mul_f32_e32 v48, 0x4b800000, v54
	v_cmp_gt_f32_e32 vcc, s21, v54
	v_fma_f32 v37, v38, v37, v42
	v_fma_f32 v38, v39, v46, v43
	v_fma_f32 v39, v40, v47, v44
	v_fmac_f32_e32 v45, v41, v36
	v_fmac_f32_e32 v37, v74, v69
	v_fmac_f32_e32 v38, v74, v66
	v_fmac_f32_e32 v39, v74, v70
	v_fmac_f32_e32 v45, v74, v67
	v_mul_f32_e32 v36, v37, v76
	v_mul_f32_e32 v37, v38, v60
	v_mul_f32_e32 v38, v39, v62
	v_mul_f32_e32 v39, v45, v61
	v_cvt_pk_bf16_f32 v36, v36, v37
	v_cvt_pk_bf16_f32 v37, v38, v39
	global_store_dwordx2 v[30:31], v[36:37], off
	s_nop 1
	v_mov_b32_e32 v36, v164
	v_mov_b32_e32 v37, v165
	v_mov_b32_e32 v38, v166
	v_mov_b32_e32 v39, v167
	s_nop 0
	v_mov_b32_e32 v40, v168
	v_mov_b32_e32 v41, v169
	v_mov_b32_e32 v42, v170
	v_mov_b32_e32 v43, v171
	v_cndmask_b32_e32 v48, v54, v48, vcc
	v_rsq_f32_e32 v48, v48
	v_lshlrev_b32_e32 v44, 16, v32
	v_and_b32_e32 v32, 0xffff0000, v32
	v_lshlrev_b32_e32 v45, 16, v33
	v_mul_f32_e32 v49, 0x45800000, v48
	v_cndmask_b32_e32 v48, v48, v49, vcc
	v_mul_f32_e32 v49, v50, v48
	v_mul_f32_e32 v50, v52, v48
	v_mul_f32_e32 v51, v51, v48
	v_mul_f32_e32 v48, v53, v48
	v_and_b32_e32 v33, 0xffff0000, v33
	v_lshlrev_b32_e32 v46, 16, v34
	v_and_b32_e32 v34, 0xffff0000, v34
	v_lshlrev_b32_e32 v47, 16, v35
	v_and_b32_e32 v35, 0xffff0000, v35
	v_fma_f32 v36, v36, v49, v40
	v_fma_f32 v37, v37, v50, v41
	v_fma_f32 v38, v38, v51, v42
	v_fmac_f32_e32 v43, v39, v48
	v_fmac_f32_e32 v36, v75, v44
	v_fmac_f32_e32 v37, v75, v32
	v_fmac_f32_e32 v38, v75, v45
	v_fmac_f32_e32 v43, v75, v33
	v_mul_f32_e32 v32, v36, v46
	v_mul_f32_e32 v33, v37, v34
	v_mul_f32_e32 v34, v38, v47
	v_mul_f32_e32 v35, v43, v35
	v_cvt_pk_bf16_f32 v32, v32, v33
	v_cvt_pk_bf16_f32 v33, v34, v35
	global_store_dwordx2 v[30:31], v[32:33], off offset:512
	s_andn2_b64 exec, exec, s[18:19]
	s_cbranch_execnz .LBB0_628
